# stack + next-tile K/V staging issued between the two 32-key halves instead of right after the tile barrier
# speedup vs baseline: 1.0002x; 1.0002x over previous
.LBB0_887:
	v_lshl_add_u32 v203, s68, 6, v202
	v_exp_f32_e32 v209, v80
	v_exp_f32_e32 v211, v81
	v_exp_f32_e32 v213, v82
	v_exp_f32_e32 v215, v83
	ds_read_b128 v[80:83], v203 offset:13312
	ds_read_b128 v[204:207], v203 offset:17920
	v_exp_f32_e32 v217, v84
	v_exp_f32_e32 v219, v85
	v_exp_f32_e32 v221, v86
	v_exp_f32_e32 v223, v87
	v_exp_f32_e32 v208, v64
	v_exp_f32_e32 v210, v65
	v_exp_f32_e32 v212, v66
	v_exp_f32_e32 v214, v67
	v_exp_f32_e32 v216, v68
	v_exp_f32_e32 v218, v69
	v_exp_f32_e32 v220, v70
	v_exp_f32_e32 v222, v71
	v_cvt_pk_bf16_f32 v64, v209, v211
	v_cvt_pk_bf16_f32 v65, v213, v215
	v_cvt_pk_bf16_f32 v66, v217, v219
	v_cvt_pk_bf16_f32 v67, v221, v223
	v_cvt_pk_bf16_f32 v68, v208, v210
	v_cvt_pk_bf16_f32 v69, v212, v214
	v_cvt_pk_bf16_f32 v70, v216, v218
	v_cvt_pk_bf16_f32 v71, v220, v222
	ds_read_b128 v[84:87], v203 offset:13344
	s_waitcnt lgkmcnt(0)
	v_mfma_f32_32x32x16_bf16 v[48:63], v[80:83], v[64:67], v[48:63]
	v_exp_f32_e32 v225, v88
	v_exp_f32_e32 v224, v72
	v_exp_f32_e32 v88, v73
	v_exp_f32_e32 v89, v89
	v_exp_f32_e32 v227, v90
	v_exp_f32_e32 v91, v91
	v_exp_f32_e32 v229, v92
	v_mfma_f32_32x32x16_bf16 v[16:31], v[80:83], v[68:71], v[16:31]
	ds_read_b128 v[80:83], v203 offset:17952
	v_exp_f32_e32 v93, v93
	v_exp_f32_e32 v231, v94
	v_exp_f32_e32 v95, v95
	v_exp_f32_e32 v226, v74
	v_exp_f32_e32 v90, v75
	v_exp_f32_e32 v228, v76
	v_mfma_f32_32x32x16_bf16 v[32:47], v[204:207], v[64:67], v[32:47]
	v_exp_f32_e32 v92, v77
	v_add_f32_e32 v64, v210, v208
	v_add_f32_e32 v65, v211, v209
	v_exp_f32_e32 v230, v78
	v_add_f32_e32 v208, v212, v64
	v_add_f32_e32 v209, v213, v65
	v_exp_f32_e32 v94, v79
	v_add_f32_e32 v72, v214, v208
	v_add_f32_e32 v73, v215, v209
	v_mfma_f32_32x32x16_bf16 v[0:15], v[204:207], v[68:71], v[0:15]
	v_add_f32_e64 v72, v216, v72
	v_add_f32_e64 v73, v217, v73
	v_cvt_pk_bf16_f32 v64, v225, v89
	v_add_f32_e64 v72, v218, v72
	v_add_f32_e64 v73, v219, v73
	v_cvt_pk_bf16_f32 v65, v227, v91
	v_add_f32_e32 v72, v220, v72
	v_add_f32_e32 v73, v221, v73
	v_cvt_pk_bf16_f32 v66, v229, v93
	v_add_f32_e32 v72, v222, v72
	v_add_f32_e32 v73, v223, v73
	v_cvt_pk_bf16_f32 v67, v231, v95
	v_cvt_pk_bf16_f32 v68, v224, v88
	v_cvt_pk_bf16_f32 v69, v226, v90
	v_cvt_pk_bf16_f32 v70, v228, v92
	v_cvt_pk_bf16_f32 v71, v230, v94
	v_add_f32_e32 v72, v224, v72
	v_add_f32_e32 v73, v225, v73
	v_mfma_f32_32x32x16_bf16 v[48:63], v[84:87], v[64:67], v[48:63]
	v_add_f32_e64 v72, v88, v72
	v_add_f32_e64 v73, v89, v73
	s_xor_b64 s[28:29], s[66:67], -1
	s_mov_b32 s68, 1
	s_mov_b64 s[66:67], 0
	s_and_b64 vcc, exec, s[28:29]
	v_mfma_f32_32x32x16_bf16 v[16:31], v[84:87], v[68:71], v[16:31]
	s_waitcnt lgkmcnt(0)
	v_mfma_f32_32x32x16_bf16 v[32:47], v[80:83], v[64:67], v[32:47]
	v_add_f32_e64 v64, v226, v72
	v_add_f32_e64 v65, v227, v73
	v_add_f32_e64 v64, v90, v64
	v_add_f32_e64 v65, v91, v65
	v_add_f32_e64 v64, v228, v64
	v_add_f32_e64 v65, v229, v65
	v_add_f32_e32 v64, v92, v64
	v_add_f32_e32 v65, v93, v65
	v_mfma_f32_32x32x16_bf16 v[0:15], v[80:83], v[68:71], v[0:15]
	v_add_f32_e64 v64, v230, v64
	v_add_f32_e64 v65, v231, v65
	v_add_f32_e64 v64, v94, v64
	v_add_f32_e64 v65, v95, v65
	v_add_f32_e64 v150, v150, v64
	v_add_f32_e64 v151, v151, v65
	s_cbranch_vccnz .LBB0_889
	s_cmp_ge_u32 s88, s87
	s_cbranch_scc1 .Lhwat0_dskip
	s_cmp_eq_u32 s88, 1
	s_cbranch_scc1 .Lhwat0_dskip
	s_mov_b64 s[28:29], 0x80
	s_add_u32 m0, s98, s35
	v_lshl_add_u64 v[152:153], v[152:153], 0, v[154:155]
	global_load_lds_dwordx4 v[152:153], off
	s_add_u32 m0, s99, s35
	v_lshl_add_u64 v[158:159], v[158:159], 0, v[160:161]
	global_load_lds_dwordx4 v[158:159], off
	s_add_u32 m0, s100, s35
	v_lshl_add_u64 v[164:165], v[164:165], 0, v[166:167]
	global_load_lds_dwordx4 v[164:165], off
	s_add_u32 s30, s98, s35
	s_add_u32 m0, s30, 0x3400
	v_lshl_add_u64 v[176:177], v[176:177], 0, s[28:29]
	global_load_lds_dwordx4 v[176:177], off
	s_add_u32 s30, s99, s35
	s_add_u32 m0, s30, 0x3400
	v_lshl_add_u64 v[180:181], v[180:181], 0, s[28:29]
	global_load_lds_dwordx4 v[180:181], off
	s_and_saveexec_b64 vcc, s[10:11]
	s_cbranch_execz .Lhwat0_dtail
	s_add_u32 m0, s101, s35
	v_lshl_add_u64 v[170:171], v[170:171], 0, v[172:173]
	global_load_lds_dwordx4 v[170:171], off
	s_add_u32 s30, s100, s35
	s_add_u32 m0, s30, 0x3400
	v_lshl_add_u64 v[148:149], v[148:149], 0, s[28:29]
	global_load_lds_dwordx4 v[148:149], off
.Lhwat0_dtail:
	s_or_b64 exec, exec, vcc
.Lhwat0_dskip:
	s_mov_b64 s[64:65], 0
	s_and_b64 vcc, exec, s[62:63]
	v_lshl_or_b32 v203, s68, 5, v190
	s_mov_b64 s[28:29], -1
	s_cbranch_vccz .LBB0_882
	s_branch .LBB0_883

.LBB0_2121:
	v_lshl_add_u32 v203, s68, 6, v202
	v_exp_f32_e32 v209, v80
	v_exp_f32_e32 v211, v81
	v_exp_f32_e32 v213, v82
	v_exp_f32_e32 v215, v83
	ds_read_b128 v[80:83], v203 offset:13312
	ds_read_b128 v[204:207], v203 offset:17920
	v_exp_f32_e32 v217, v84
	v_exp_f32_e32 v219, v85
	v_exp_f32_e32 v221, v86
	v_exp_f32_e32 v223, v87
	v_exp_f32_e32 v208, v64
	v_exp_f32_e32 v210, v65
	v_exp_f32_e32 v212, v66
	v_exp_f32_e32 v214, v67
	v_exp_f32_e32 v216, v68
	v_exp_f32_e32 v218, v69
	v_exp_f32_e32 v220, v70
	v_exp_f32_e32 v222, v71
	v_cvt_pk_bf16_f32 v64, v209, v211
	v_cvt_pk_bf16_f32 v65, v213, v215
	v_cvt_pk_bf16_f32 v66, v217, v219
	v_cvt_pk_bf16_f32 v67, v221, v223
	v_cvt_pk_bf16_f32 v68, v208, v210
	v_cvt_pk_bf16_f32 v69, v212, v214
	v_cvt_pk_bf16_f32 v70, v216, v218
	v_cvt_pk_bf16_f32 v71, v220, v222
	ds_read_b128 v[84:87], v203 offset:13344
	s_waitcnt lgkmcnt(0)
	v_mfma_f32_32x32x16_bf16 v[48:63], v[80:83], v[64:67], v[48:63]
	v_exp_f32_e32 v225, v88
	v_exp_f32_e32 v224, v72
	v_exp_f32_e32 v88, v73
	v_exp_f32_e32 v89, v89
	v_exp_f32_e32 v227, v90
	v_exp_f32_e32 v91, v91
	v_exp_f32_e32 v229, v92
	v_mfma_f32_32x32x16_bf16 v[16:31], v[80:83], v[68:71], v[16:31]
	ds_read_b128 v[80:83], v203 offset:17952
	v_exp_f32_e32 v93, v93
	v_exp_f32_e32 v231, v94
	v_exp_f32_e32 v95, v95
	v_exp_f32_e32 v226, v74
	v_exp_f32_e32 v90, v75
	v_exp_f32_e32 v228, v76
	v_mfma_f32_32x32x16_bf16 v[32:47], v[204:207], v[64:67], v[32:47]
	v_exp_f32_e32 v92, v77
	v_add_f32_e32 v64, v210, v208
	v_add_f32_e32 v65, v211, v209
	v_exp_f32_e32 v230, v78
	v_add_f32_e32 v208, v212, v64
	v_add_f32_e32 v209, v213, v65
	v_exp_f32_e32 v94, v79
	v_add_f32_e32 v72, v214, v208
	v_add_f32_e32 v73, v215, v209
	v_mfma_f32_32x32x16_bf16 v[0:15], v[204:207], v[68:71], v[0:15]
	v_add_f32_e64 v72, v216, v72
	v_add_f32_e64 v73, v217, v73
	v_cvt_pk_bf16_f32 v64, v225, v89
	v_add_f32_e64 v72, v218, v72
	v_add_f32_e64 v73, v219, v73
	v_cvt_pk_bf16_f32 v65, v227, v91
	v_add_f32_e32 v72, v220, v72
	v_add_f32_e32 v73, v221, v73
	v_cvt_pk_bf16_f32 v66, v229, v93
	v_add_f32_e32 v72, v222, v72
	v_add_f32_e32 v73, v223, v73
	v_cvt_pk_bf16_f32 v67, v231, v95
	v_cvt_pk_bf16_f32 v68, v224, v88
	v_cvt_pk_bf16_f32 v69, v226, v90
	v_cvt_pk_bf16_f32 v70, v228, v92
	v_cvt_pk_bf16_f32 v71, v230, v94
	v_add_f32_e32 v72, v224, v72
	v_add_f32_e32 v73, v225, v73
	v_mfma_f32_32x32x16_bf16 v[48:63], v[84:87], v[64:67], v[48:63]
	v_add_f32_e64 v72, v88, v72
	v_add_f32_e64 v73, v89, v73
	s_xor_b64 s[34:35], s[66:67], -1
	s_mov_b32 s68, 1
	s_mov_b64 s[66:67], 0
	s_and_b64 vcc, exec, s[34:35]
	v_mfma_f32_32x32x16_bf16 v[16:31], v[84:87], v[68:71], v[16:31]
	s_waitcnt lgkmcnt(0)
	v_mfma_f32_32x32x16_bf16 v[32:47], v[80:83], v[64:67], v[32:47]
	v_add_f32_e64 v64, v226, v72
	v_add_f32_e64 v65, v227, v73
	v_add_f32_e64 v64, v90, v64
	v_add_f32_e64 v65, v91, v65
	v_add_f32_e64 v64, v228, v64
	v_add_f32_e64 v65, v229, v65
	v_add_f32_e32 v64, v92, v64
	v_add_f32_e32 v65, v93, v65
	v_mfma_f32_32x32x16_bf16 v[0:15], v[80:83], v[68:71], v[0:15]
	v_add_f32_e64 v64, v230, v64
	v_add_f32_e64 v65, v231, v65
	v_add_f32_e64 v64, v94, v64
	v_add_f32_e64 v65, v95, v65
	v_add_f32_e64 v150, v150, v64
	v_add_f32_e64 v151, v151, v65
	s_cbranch_vccnz .LBB0_2123
	s_cmp_ge_u32 s87, s86
	s_cbranch_scc1 .Lhwat1_dskip
	s_cmp_eq_u32 s87, 1
	s_cbranch_scc1 .Lhwat1_dskip
	s_mov_b64 s[34:35], 0x80
	s_add_u32 m0, s98, s89
	v_lshl_add_u64 v[152:153], v[152:153], 0, v[154:155]
	global_load_lds_dwordx4 v[152:153], off
	s_add_u32 m0, s99, s89
	v_lshl_add_u64 v[158:159], v[158:159], 0, v[160:161]
	global_load_lds_dwordx4 v[158:159], off
	s_add_u32 m0, s100, s89
	v_lshl_add_u64 v[164:165], v[164:165], 0, v[166:167]
	global_load_lds_dwordx4 v[164:165], off
	s_add_u32 s30, s98, s89
	s_add_u32 m0, s30, 0x3400
	v_lshl_add_u64 v[176:177], v[176:177], 0, s[34:35]
	global_load_lds_dwordx4 v[176:177], off
	s_add_u32 s30, s99, s89
	s_add_u32 m0, s30, 0x3400
	v_lshl_add_u64 v[180:181], v[180:181], 0, s[34:35]
	global_load_lds_dwordx4 v[180:181], off
	s_and_saveexec_b64 vcc, s[12:13]
	s_cbranch_execz .Lhwat1_dtail
	s_add_u32 m0, s101, s89
	v_lshl_add_u64 v[170:171], v[170:171], 0, v[172:173]
	global_load_lds_dwordx4 v[170:171], off
	s_add_u32 s30, s100, s89
	s_add_u32 m0, s30, 0x3400
	v_lshl_add_u64 v[148:149], v[148:149], 0, s[34:35]
	global_load_lds_dwordx4 v[148:149], off

.Lhwat1_dskip:
	s_mov_b64 s[64:65], 0
	s_and_b64 vcc, exec, s[62:63]
	v_lshl_or_b32 v203, s68, 5, v190
	s_mov_b64 s[34:35], -1
	s_cbranch_vccz .LBB0_2116
	s_branch .LBB0_2117
